# GEMM load segments issue LDS-DMA before ds_reads, setprio toggles removed, scan pass B writes output tiles transposed as one dwordx2 per tile
# baseline (speedup 1.0000x reference)
.LBB0_629:
	s_or_b64 exec, exec, s[30:31]
	v_cmp_le_i32_e32 vcc, v130, v128
	v_cmp_lt_i32_e64 s[0:1], v130, v128
	s_and_b64 s[30:31], s[50:51], vcc
	s_or_b64 s[36:37], s[76:77], s[30:31]
	s_and_b64 s[30:31], s[50:51], s[0:1]
	v_cndmask_b32_e64 v80, 0, v80, s[36:37]
	s_or_b64 s[36:37], s[76:77], s[30:31]
	s_and_b64 s[30:31], s[74:75], vcc
	v_cndmask_b32_e64 v81, 0, v81, s[36:37]
	s_or_b64 s[36:37], s[58:59], s[30:31]
	s_and_b64 s[30:31], s[74:75], s[0:1]
	v_cndmask_b32_e64 v76, 0, v76, s[36:37]
	s_or_b64 s[36:37], s[58:59], s[30:31]
	s_and_b64 s[30:31], s[56:57], vcc
	v_cndmask_b32_e64 v77, 0, v77, s[36:37]
	s_or_b64 s[36:37], s[52:53], s[30:31]
	s_and_b64 s[30:31], s[56:57], s[0:1]
	v_cndmask_b32_e64 v72, 0, v72, s[36:37]
	s_or_b64 s[36:37], s[52:53], s[30:31]
	s_and_b64 s[30:31], s[38:39], vcc
	s_or_b64 vcc, s[18:19], s[30:31]
	s_and_b64 s[0:1], s[38:39], s[0:1]
	v_cndmask_b32_e32 v68, 0, v68, vcc
	s_or_b64 vcc, s[18:19], s[0:1]
	v_cndmask_b32_e64 v73, 0, v73, s[36:37]
	v_cndmask_b32_e32 v69, 0, v69, vcc
	v_cvt_pk_bf16_f32 v68, v68, v69
	v_cvt_pk_bf16_f32 v69, v84, v70
	v_cvt_pk_bf16_f32 v70, v72, v73
	v_cvt_pk_bf16_f32 v71, v71, v74
	v_cvt_pk_bf16_f32 v72, v76, v77
	v_cvt_pk_bf16_f32 v73, v75, v78
	v_cvt_pk_bf16_f32 v74, v80, v81
	v_cvt_pk_bf16_f32 v75, v79, v82
	ds_read_b128 v[76:79], v88
	ds_read_b128 v[80:83], v88 offset:64
	ds_read_b128 v[84:87], v88 offset:128
	ds_read_b128 v[88:91], v88 offset:192
	s_movk_i32 s0, 0x480
	v_mul_lo_u32 v93, v187, s0
	v_ashrrev_i32_e32 v131, 31, v130
	v_add_u32_e32 v93, s88, v93
	v_mul_lo_u32 v94, v188, s20
	v_add3_u32 v94, v93, v94, v92
	v_lshl_add_u64 v[92:93], s[8:9], 0, v[130:131]
	v_ashrrev_i32_e32 v129, 31, v128
	v_lshlrev_b64 v[92:93], 11, v[92:93]
	v_lshl_add_u64 v[92:93], v[128:129], 1, v[92:93]
	v_lshl_add_u64 v[92:93], s[2:3], 0, v[92:93]
	v_and_b32_e32 v132, 15, v210
	v_bfe_u32 v133, v210, 4, 2
	v_lshlrev_b32_e32 v133, 2, v133
	v_sub_u32_e32 v132, v132, v133
	v_mul_i32_i24_e32 v132, 0x7fe, v132
	v_ashrrev_i32_e32 v133, 31, v132
	v_lshl_add_u64 v[92:93], v[92:93], 0, v[132:133]
	v_add3_u32 v95, s91, v185, v95
	s_mov_b64 s[0:1], 0
.LBB0_630:
	v_add_u32_e32 v136, 0, v95
	ds_read_b128 v[96:99], v136
	ds_read_b128 v[128:131], v136 offset:64
	v_add_u32_e32 v137, 0, v94
	s_brev_b32 s30, 52
	v_add_u32_e32 v94, 64, v94
	s_waitcnt lgkmcnt(1)
	v_mfma_f32_16x16x32_bf16 v[96:99], v[96:99], v[76:79], 0
	v_add_u32_e32 v95, 0x2200, v95
	s_waitcnt lgkmcnt(0)
	v_mfma_f32_16x16x32_bf16 v[96:99], v[128:131], v[80:83], v[96:99]
	ds_read_b128 v[128:131], v136 offset:128
	s_waitcnt lgkmcnt(0)
	v_mfma_f32_16x16x32_bf16 v[96:99], v[128:131], v[84:87], v[96:99]
	ds_read_b128 v[128:131], v136 offset:192
	s_waitcnt lgkmcnt(0)
	v_mfma_f32_16x16x32_bf16 v[96:99], v[128:131], v[88:91], v[96:99]
	v_add_u32_e32 v128, 0x17600, v137
	v_add_u32_e32 v130, 0x18800, v137
	ds_read_b64_tr_b16 v[128:129], v128
	ds_read_b64_tr_b16 v[130:131], v130
	s_waitcnt lgkmcnt(0)
	v_mfma_f32_16x16x32_bf16 v[96:99], v[128:131], v[68:71], v[96:99]
	v_add_u32_e32 v128, 0x19a00, v137
	v_add_u32_e32 v130, 0x1ac00, v137
	ds_read_b64_tr_b16 v[128:129], v128
	ds_read_b64_tr_b16 v[130:131], v130
	s_waitcnt lgkmcnt(0)
	v_mfma_f32_16x16x32_bf16 v[96:99], v[128:131], v[72:75], v[96:99]
	v_lshl_add_u64 v[128:129], v[92:93], 0, s[0:1]
	v_add_co_u32_e32 v132, vcc, s30, v128
	s_mov_b32 s30, 0x2c001000
	s_nop 0
	v_addc_co_u32_e32 v133, vcc, 0, v129, vcc
	v_add_co_u32_e32 v134, vcc, s30, v128
	s_nop 1
	v_cvt_pk_bf16_f32 v96, v96, v97
	v_addc_co_u32_e32 v135, vcc, 0, v129, vcc
	v_cvt_pk_bf16_f32 v97, v98, v99
	global_store_dwordx2 v[134:135], v[96:97], off offset:-4096
	ds_read_b128 v[96:99], v136 offset:4352
	ds_read_b128 v[128:131], v136 offset:4416
	s_waitcnt lgkmcnt(1)
	v_mfma_f32_16x16x32_bf16 v[96:99], v[96:99], v[76:79], 0
	s_add_u32 s0, s0, 64
	s_addc_u32 s1, s1, 0
	s_cmpk_eq_i32 s0, 0x80
	s_waitcnt lgkmcnt(0)
	v_mfma_f32_16x16x32_bf16 v[96:99], v[128:131], v[80:83], v[96:99]
	ds_read_b128 v[128:131], v136 offset:4480
	s_waitcnt lgkmcnt(0)
	v_mfma_f32_16x16x32_bf16 v[96:99], v[128:131], v[84:87], v[96:99]
	ds_read_b128 v[128:131], v136 offset:4544
	s_waitcnt lgkmcnt(0)
	v_mfma_f32_16x16x32_bf16 v[96:99], v[128:131], v[88:91], v[96:99]
	v_add_u32_e32 v128, 0x17620, v137
	v_add_u32_e32 v130, 0x18820, v137
	ds_read_b64_tr_b16 v[128:129], v128
	ds_read_b64_tr_b16 v[130:131], v130
	s_waitcnt lgkmcnt(0)
	v_mfma_f32_16x16x32_bf16 v[96:99], v[128:131], v[68:71], v[96:99]
	v_add_u32_e32 v128, 0x19a20, v137
	v_add_u32_e32 v130, 0x1ac20, v137
	ds_read_b64_tr_b16 v[128:129], v128
	ds_read_b64_tr_b16 v[130:131], v130
	s_waitcnt lgkmcnt(0)
	v_mfma_f32_16x16x32_bf16 v[96:99], v[128:131], v[72:75], v[96:99]
	s_nop 7
	v_cvt_pk_bf16_f32 v96, v96, v97
	v_cvt_pk_bf16_f32 v97, v98, v99
	global_store_dwordx2 v[132:133], v[96:97], off offset:32
	s_cbranch_scc0 .LBB0_630
	v_add_u32_e32 v70, 0, v172
	v_cvt_pk_bf16_f32 v68, v12, v13
	v_cvt_pk_bf16_f32 v69, v14, v15
	v_add_u32_e32 v71, v70, v185
	s_waitcnt lgkmcnt(0)
	s_barrier
	ds_write_b64 v71, v[68:69] offset:60928
	v_cvt_pk_bf16_f32 v68, v16, v17
	v_cvt_pk_bf16_f32 v69, v18, v19
	ds_write_b64 v71, v[68:69] offset:65280
	v_cvt_pk_bf16_f32 v68, v24, v25
	v_cvt_pk_bf16_f32 v69, v26, v27
	v_add_u32_e32 v70, v70, v186
	ds_write_b64 v70, v[68:69] offset:60928
	v_cvt_pk_bf16_f32 v68, v32, v33
	v_cvt_pk_bf16_f32 v69, v34, v35
	v_add_u32_e32 v72, 0xee00, v71
	ds_write_b64 v70, v[68:69] offset:65280
	v_cvt_pk_bf16_f32 v68, v20, v21
	v_cvt_pk_bf16_f32 v69, v22, v23
	ds_write_b64 v72, v[68:69] offset:17408
	v_cvt_pk_bf16_f32 v68, v28, v29
	v_cvt_pk_bf16_f32 v69, v30, v31
	ds_write_b64 v72, v[68:69] offset:21760
	v_cvt_pk_bf16_f32 v68, v36, v37
	v_cvt_pk_bf16_f32 v69, v38, v39
	ds_write_b64 v72, v[68:69] offset:26112
	v_cvt_pk_bf16_f32 v68, v40, v41
	v_cvt_pk_bf16_f32 v69, v42, v43
	ds_write_b64 v72, v[68:69] offset:30464
	v_mov_b32_e32 v68, v164
	s_add_u32 s8, s8, 64
	v_ashrrev_i32_e32 v69, 4, v68
	v_add_u32_e32 v71, 32, v69
	v_lshrrev_b32_e32 v70, 6, v68
	v_lshrrev_b32_e32 v71, 2, v71
	v_and_b32_e32 v70, 14, v70
	v_and_b32_e32 v71, 14, v71
	v_add_lshl_u32 v70, v70, v68, 4
	v_add_lshl_u32 v71, v71, v68, 4
	v_lshlrev_b32_e32 v68, 4, v68
	v_mul_lo_u32 v72, v69, s20
	v_and_b32_e32 v68, 0xf0, v68
	v_add3_u32 v72, s60, v72, v68
	v_and_b32_e32 v70, 0xf0, v70
	s_waitcnt vmcnt(12)
	ds_write_b128 v72, v[52:55]
	s_waitcnt vmcnt(10)
	ds_write_b128 v72, v[64:67] offset:9216
	v_mul_lo_u32 v52, v69, s61
	v_add3_u32 v53, s66, v52, v70
	v_and_b32_e32 v71, 0xf0, v71
	ds_write_b128 v53, v[44:47]
	v_add_u32_e32 v44, 0x2200, v52
	v_add3_u32 v45, s66, v44, v71
	s_addc_u32 s9, s9, 0
	ds_write_b128 v45, v[48:51]
	v_add3_u32 v45, s64, v52, v68
	v_add3_u32 v44, s64, v44, v68
	s_cmp_eq_u32 s94, 16
	s_waitcnt vmcnt(9)
	ds_write_b128 v45, v[56:59]
	s_waitcnt vmcnt(8)
	ds_write_b128 v44, v[60:63]
	s_cbranch_scc0 .LBB0_606
	s_branch .LBB0_641
